# attention phase B: second half-step's staging also retires the register-stage loads issued just before it (strict alternation of the two waves of a SIMD)
# speedup vs baseline: 1.0012x; 1.0002x over previous
.LBB0_555:
	s_add_i32 s67, s67, 1
	s_and_b64 s[0:1], s[38:39], exec
	s_cselect_b32 s14, s66, s67
	s_and_b64 s[0:1], s[18:19], exec
	s_cselect_b32 s78, s67, s14
	s_xor_b64 s[0:1], s[18:19], -1
	v_cndmask_b32_e64 v2, 0, 1, s[0:1]
	s_waitcnt vmcnt(14)
	ds_write_b128 v219, v[48:51]
	s_waitcnt vmcnt(12)
	ds_write_b128 v219, v[60:63] offset:1152
	s_waitcnt vmcnt(10)
	ds_write_b128 v219, v[80:83] offset:2304
	s_waitcnt vmcnt(8)
	ds_write_b128 v219, v[92:95] offset:3456
	s_waitcnt vmcnt(6)
	ds_write_b128 v219, v[100:103] offset:4608
	s_waitcnt vmcnt(4)
	ds_write_b128 v219, v[108:111] offset:5760
	s_waitcnt vmcnt(2)
	ds_write_b128 v219, v[116:119] offset:6912
	s_waitcnt vmcnt(0)
	ds_write_b128 v219, v[124:127] offset:8064
	ds_write_b128 v220, v[56:59] offset:9216
	ds_write_b128 v220, v[72:75] offset:10240
	ds_write_b128 v220, v[84:87] offset:11264
	ds_write_b128 v220, v[96:99] offset:12288
	ds_write_b128 v220, v[104:107] offset:13312
	ds_write_b128 v220, v[112:115] offset:14336
	ds_write_b128 v220, v[120:123] offset:15360
	s_setprio 1
	ds_write_b128 v220, v[128:131] offset:16384
	v_readfirstlane_b32 s0, v2
	s_add_i32 s67, s77, s0
	s_cmp_eq_u32 s67, 1
	s_cselect_b32 s0, 2, 4
	s_lshl_b32 s20, s78, 6
	s_lshr_b32 s1, 16, s0
	s_sub_i32 s18, 0x80, s20
	s_lshr_b32 s0, s8, s0
	ds_read_b128 v[60:63], v228 offset:9216
	ds_read_b128 v[72:75], v229 offset:9216
	ds_read_b128 v[56:59], v230 offset:9728
	ds_read_b128 v[48:51], v231 offset:9728
	s_sub_i32 s21, s18, s0
	v_mul_u32_u24_e32 v2, s1, v173
	v_mov_b32_e32 v3, s18
	s_cmp_lg_u32 s67, 2
	v_mad_u32_u24 v3, s1, v173, v3
	s_cselect_b64 s[0:1], -1, 0
	s_cmp_lg_u32 s78, 2
	v_subrev_u32_e32 v2, s20, v2
	s_cselect_b64 s[18:19], -1, 0
	v_max_i32_e32 v80, s21, v2
	s_or_b64 s[0:1], s[0:1], s[18:19]
	v_sub_u32_e32 v2, v3, v80
	v_sub_u32_e32 v85, v176, v80
	s_mov_b64 s[14:15], -1
	s_and_b64 vcc, exec, s[0:1]
	v_cmp_le_u32_e64 s[0:1], v85, v2
	v_add_u32_e32 v86, 1, v85
	v_add_u32_e32 v84, 2, v85
	v_add_u32_e32 v83, 3, v85
	v_add_u32_e32 v82, 4, v85
	v_add_u32_e32 v81, 5, v85
	v_add_u32_e32 v80, 6, v85
	v_add_u32_e32 v3, 7, v85
	s_cbranch_vccz .LBB0_557
	s_waitcnt vmcnt(17) lgkmcnt(3)
	v_mfma_f32_16x16x32_bf16 v[92:95], v[60:63], v[132:135], 0
	ds_read_b128 v[96:99], v228 offset:13312
	ds_read_b128 v[100:103], v229 offset:13312
	v_cmp_le_u32_e32 vcc, v86, v2
	ds_read_b128 v[104:107], v230 offset:13824
	ds_read_b128 v[108:111], v231 offset:13824
	s_waitcnt vmcnt(16) lgkmcnt(6)
	v_mfma_f32_16x16x32_bf16 v[92:95], v[72:75], v[136:139], v[92:95]
	s_mov_b64 s[14:15], 0
	s_waitcnt lgkmcnt(5)
	v_mfma_f32_16x16x32_bf16 v[112:115], v[56:59], v[132:135], 0
	s_waitcnt lgkmcnt(4)
	v_mfma_f32_16x16x32_bf16 v[112:115], v[48:51], v[136:139], v[112:115]
	s_nop 2
	v_cndmask_b32_e32 v116, v217, v93, vcc
	v_cmp_le_u32_e32 vcc, v84, v2
	v_cndmask_b32_e64 v87, v217, v92, s[0:1]
	s_nop 0
	v_cndmask_b32_e32 v117, v217, v94, vcc
	v_cmp_le_u32_e32 vcc, v83, v2
	s_nop 1
	v_cndmask_b32_e32 v118, v217, v95, vcc
	s_waitcnt lgkmcnt(3)
	v_mfma_f32_16x16x32_bf16 v[92:95], v[96:99], v[132:135], 0
	v_cmp_le_u32_e32 vcc, v82, v2
	s_nop 1
	v_cndmask_b32_e32 v112, v217, v112, vcc
	v_cmp_le_u32_e32 vcc, v81, v2
	s_waitcnt lgkmcnt(2)
	v_mfma_f32_16x16x32_bf16 v[92:95], v[100:103], v[136:139], v[92:95]
	v_add_u32_e32 v101, 32, v85
	v_cndmask_b32_e32 v113, v217, v113, vcc
	v_cmp_le_u32_e32 vcc, v80, v2
	s_waitcnt lgkmcnt(1)
	v_mfma_f32_16x16x32_bf16 v[96:99], v[104:107], v[132:135], 0
	v_cndmask_b32_e32 v114, v217, v114, vcc
	v_cmp_le_u32_e32 vcc, v3, v2
	s_waitcnt lgkmcnt(0)
	v_mfma_f32_16x16x32_bf16 v[96:99], v[108:111], v[136:139], v[96:99]
	v_cndmask_b32_e32 v100, v217, v115, vcc
	v_cmp_le_u32_e32 vcc, v101, v2
	v_add_u32_e32 v101, 33, v85
	s_nop 0
	v_cndmask_b32_e32 v92, v217, v92, vcc
	v_cmp_le_u32_e32 vcc, v101, v2
	v_add_u32_e32 v101, 34, v85
	s_nop 0
	v_cndmask_b32_e32 v93, v217, v93, vcc
	v_cmp_le_u32_e32 vcc, v101, v2
	v_add_u32_e32 v101, 35, v85
	s_nop 0
	v_cndmask_b32_e32 v94, v217, v94, vcc
	v_cmp_le_u32_e32 vcc, v101, v2
	v_add_u32_e32 v101, 36, v85
	s_nop 0
	v_cndmask_b32_e32 v95, v217, v95, vcc
	v_cmp_le_u32_e32 vcc, v101, v2
	v_add_u32_e32 v101, 37, v85
	s_nop 0
	v_cndmask_b32_e32 v96, v217, v96, vcc
	v_cmp_le_u32_e32 vcc, v101, v2
	v_add_u32_e32 v101, 38, v85
	s_nop 0
	v_cndmask_b32_e32 v97, v217, v97, vcc
	v_cmp_le_u32_e32 vcc, v101, v2
	v_add_u32_e32 v101, 39, v85
	s_nop 0
	v_cndmask_b32_e32 v98, v217, v98, vcc
	v_cmp_le_u32_e32 vcc, v101, v2
	v_max3_f32 v101, v87, s62, v116
	v_max3_f32 v101, v101, v117, v118
	v_max3_f32 v101, v101, v112, v113
	v_max3_f32 v101, v101, v114, v100
	v_max3_f32 v101, v101, v92, v93
	v_max3_f32 v101, v101, v94, v95
	v_cndmask_b32_e32 v99, v217, v99, vcc
	v_max3_f32 v101, v101, v96, v97
	v_max3_f32 v101, v101, v98, v99
	ds_bpermute_b32 v102, v0, v101
	s_waitcnt lgkmcnt(0)
	v_max_f32_e32 v102, v102, v102
	v_max_f32_e32 v101, v101, v102
	ds_bpermute_b32 v102, v222, v101
	s_waitcnt lgkmcnt(0)
	v_max3_f32 v223, v226, v101, v102
	v_sub_f32_e32 v87, v87, v223
	v_exp_f32_e32 v87, v87
	v_sub_f32_e32 v102, v116, v223
	v_exp_f32_e32 v102, v102
	v_sub_f32_e32 v103, v117, v223
	v_sub_f32_e32 v92, v92, v223
	v_exp_f32_e32 v103, v103
	v_sub_f32_e32 v104, v118, v223
	v_exp_f32_e32 v130, v92
	v_sub_f32_e32 v92, v93, v223
	v_exp_f32_e32 v104, v104
	v_sub_f32_e32 v106, v112, v223
	v_exp_f32_e32 v131, v92
	v_sub_f32_e32 v92, v94, v223
	v_add_f32_e32 v105, 0, v87
	v_exp_f32_e32 v106, v106
	v_sub_f32_e32 v107, v113, v223
	v_exp_f32_e32 v140, v92
	v_sub_f32_e32 v92, v95, v223
	v_add_f32_e32 v105, v102, v105
	v_exp_f32_e32 v107, v107
	v_sub_f32_e32 v108, v114, v223
	v_exp_f32_e32 v141, v92
	v_sub_f32_e32 v92, v96, v223
	v_add_f32_e32 v105, v103, v105
	v_exp_f32_e32 v108, v108
	v_sub_f32_e32 v100, v100, v223
	v_exp_f32_e32 v142, v92
	v_sub_f32_e32 v92, v97, v223
	v_sub_f32_e32 v101, v226, v223
	v_add_f32_e32 v105, v104, v105
	v_exp_f32_e32 v100, v100
	v_exp_f32_e32 v143, v92
	v_sub_f32_e32 v92, v98, v223
	v_add_f32_e32 v105, v106, v105
	v_exp_f32_e32 v224, v92
	v_sub_f32_e32 v116, v99, v223
	v_exp_f32_e32 v128, v101
	v_cvt_pk_bf16_f32 v92, v87, v102
	v_cvt_pk_bf16_f32 v93, v103, v104
	v_cvt_pk_bf16_f32 v94, v106, v107
	v_cvt_pk_bf16_f32 v95, v108, v100
	ds_read_b64_tr_b16 v[98:99], v225 offset:576
	ds_read_b64_tr_b16 v[96:97], v225
	v_add_f32_e32 v105, v107, v105
	v_add_f32_e32 v105, v108, v105
	v_add_f32_e32 v129, v100, v105
	ds_read_b64_tr_b16 v[106:107], v225 offset:608
	ds_read_b64_tr_b16 v[104:105], v225 offset:32
	ds_read_b64_tr_b16 v[108:109], v225 offset:64
	ds_read_b64_tr_b16 v[112:113], v225 offset:96
	ds_read_b64_tr_b16 v[110:111], v225 offset:640
	ds_read_b64_tr_b16 v[114:115], v225 offset:672
	v_pk_mul_f32 v[102:103], v[170:171], v[128:129] op_sel_hi:[1,0]
	v_pk_mul_f32 v[100:101], v[168:169], v[128:129] op_sel_hi:[1,0]
	v_exp_f32_e32 v87, v116
	v_pk_mul_f32 v[118:119], v[166:167], v[128:129] op_sel_hi:[1,0]
	s_waitcnt lgkmcnt(6)
	v_mfma_f32_16x16x32_bf16 v[96:99], v[96:99], v[92:95], v[100:103]
	v_mul_f32_e64 v116, v164, v128
	v_mul_f32_e64 v117, v165, v128
	s_nop 0
	v_pk_mul_f32 v[102:103], v[158:159], v[128:129] op_sel_hi:[1,0]
	v_pk_mul_f32 v[100:101], v[156:157], v[128:129] op_sel_hi:[1,0]
	s_waitcnt lgkmcnt(4)
	s_nop 0
	v_mfma_f32_16x16x32_bf16 v[100:103], v[104:107], v[92:95], v[100:103]
	v_mul_f32_e64 v106, v162, v128
	v_mul_f32_e64 v107, v163, v128
	v_pk_mul_f32 v[104:105], v[160:161], v[128:129] op_sel_hi:[1,0]
	s_waitcnt lgkmcnt(1)
	s_nop 0
	v_mfma_f32_16x16x32_bf16 v[104:107], v[108:111], v[92:95], v[104:107]
	v_cvt_pk_bf16_f32 v108, v130, v131
	v_cvt_pk_bf16_f32 v109, v140, v141
	v_cvt_pk_bf16_f32 v110, v142, v143
	v_cvt_pk_bf16_f32 v111, v224, v87
	ds_read_b64_tr_b16 v[122:123], v225 offset:5184
	ds_read_b64_tr_b16 v[120:121], v225 offset:4608
	s_waitcnt lgkmcnt(0)
	v_mfma_f32_16x16x32_bf16 v[152:155], v[120:123], v[108:111], v[96:99]
	s_nop 2
	v_add_f32_e32 v96, v130, v129
	v_add_f32_e32 v96, v131, v96
	v_add_f32_e32 v96, v140, v96
	v_mfma_f32_16x16x32_bf16 v[92:95], v[112:115], v[92:95], v[116:119]
	ds_read_b64_tr_b16 v[114:115], v225 offset:5216
	ds_read_b64_tr_b16 v[112:113], v225 offset:4640
	s_nop 0
	ds_read_b64_tr_b16 v[116:117], v225 offset:4672
	ds_read_b64_tr_b16 v[124:125], v225 offset:4704
	ds_read_b64_tr_b16 v[118:119], v225 offset:5248
	ds_read_b64_tr_b16 v[126:127], v225 offset:5280
	v_add_f32_e32 v96, v141, v96
	v_add_f32_e32 v96, v142, v96
	v_add_f32_e32 v96, v143, v96
	s_waitcnt lgkmcnt(0)
	v_add_f32_e32 v96, v224, v96
	v_add_f32_e32 v224, v87, v96
	s_waitcnt lgkmcnt(4)
	v_mfma_f32_16x16x32_bf16 v[148:151], v[112:115], v[108:111], v[100:103]
	v_fmac_f32_e32 v224, v227, v128
	s_waitcnt lgkmcnt(1)
	v_mfma_f32_16x16x32_bf16 v[144:147], v[116:119], v[108:111], v[104:107]
	s_waitcnt lgkmcnt(0)
	v_mfma_f32_16x16x32_bf16 v[140:143], v[124:127], v[108:111], v[92:95]
